# up-GEMM epilogue: row-sum partial reduction with 12 scalar adds (same association) instead of 18 moves + 6 packed adds
# speedup vs baseline: 1.0009x; 1.0009x over previous
; #define PG8_LAS __attribute__((address_space(3)))
; __device__ __forceinline__ float row_up1(float v) { return dpp_mov<0x111>(v); }
; __device__ __forceinline__ float siluf_(float x) { return x * __builtin_amdgcn_rcpf(1.0f + __builtin_amdgcn_exp2f(x * -1.4426950408889634f)); }
;     __device__ __forceinline__ void operator()(f32x4 (&acc)[2][2][4][2], const pg8::Unit& u, int wr, int wc, int fr, int fq) const {
;     ...
;             const int l = fq * 16 + fr, p = l >> 4, bj = (l >> 3) & 1, c4 = (l & 7) * 4;
;             const float* srcp = (p < 3 ? FW + p * NUP : FB) + bj * DFF + u.pn * 128 + wc * 32 + c4;
;             *(PG8_LAS f32x4*)(wl + l * 16) = *(const f32x4*)srcp;
;         }
; #pragma unroll
;         for (int ai = 0; ai < 2; ++ai) {
;             const int tb = u.pm * 256 + ai * 128 + wr * 64 + 4 * fr;
;             float rstd[4];
; #pragma unroll
;             for (int m = 0; m < 4; ++m) { const f32x4 sv = *(const f32x4*)(SS + (size_t)(tb + m) * 16 + 4 * fq); float s = (sv[0] + sv[1]) + (sv[2] + sv[3]); s += __shfl_xor(s, 16); s += __shfl_xor(s, 32);
;                 rstd[m] = rsqrtf(s * (1.0f / 1024.0f) + EPS); }
;             u32x2 pk[2][4];
; #pragma unroll
;             for (int n = 0; n < 2; ++n) {
;                 f32x4 g[4];
;                 {   const PG8_LAS unsigned char* wq = wl + (8 * fq + 4 * n) * 4;
;                     const f32x4 w0 = *(const PG8_LAS f32x4*)(wq), w1 = *(const PG8_LAS f32x4*)(wq + 256), w2 = *(const PG8_LAS f32x4*)(wq + 512), bb = *(const PG8_LAS f32x4*)(wq + 768);
;                     const f32x4 x0 = acc[ai][0][0][n] * rstd[0], x1 = acc[ai][0][1][n] * rstd[1], x2 = acc[ai][0][2][n] * rstd[2], x3 = acc[ai][0][3][n] * rstd[3];
;                     acc[ai][0][0][n] = x0; acc[ai][0][1][n] = x1; acc[ai][0][2][n] = x2; acc[ai][0][3][n] = x3;
;                     f32x4 p1, p2;
; #pragma unroll
;                     for (int c = 0; c < 4; ++c) { p1[c] = row_up1(x3[c]); p2[c] = row_up1(x2[c]); }
;                     g[0] = bb + w2 * x0 + w1 * p1 + w0 * p2; g[1] = bb + w2 * x1 + w1 * x0 + w0 * p1;
;                     g[2] = bb + w2 * x2 + w1 * x1 + w0 * x0; g[3] = bb + w2 * x3 + w1 * x2 + w0 * x1;
; #pragma unroll
;                     for (int m = 0; m < 4; ++m)
; #pragma unroll
;                         for (int c = 0; c < 4; ++c) g[m][c] = siluf_(g[m][c]);
.LBB0_748:
	v_lshl_add_u32 v148, s34, 8, v187
	v_ashrrev_i32_e32 v149, 31, v148
	v_lshlrev_b64 v[150:151], 6, v[148:149]
	v_lshl_add_u64 v[246:247], v[138:139], 0, v[150:151]
	v_or_b32_e32 v150, 1, v148
	global_load_dwordx4 v[160:163], v[246:247], off
	global_load_dwordx4 v[164:167], v[246:247], off offset:64
	v_or_b32_e32 v154, 2, v148
	global_load_dwordx4 v[172:175], v[246:247], off offset:128
	v_or_b32_e32 v156, 3, v148
	global_load_dwordx4 v[176:179], v[246:247], off offset:192
	s_lshl_b32 s8, s66, 7
	s_ashr_i32 s9, s8, 31
	v_lshl_add_u64 v[158:159], s[8:9], 2, v[136:137]
	global_load_dwordx4 v[180:183], v[158:159], off
	v_and_b32_e32 v151, 64, v194
	v_xor_b32_e32 v149, 16, v194
	v_add_u32_e32 v151, 64, v151
	v_cmp_lt_i32_e32 vcc, v149, v151
	v_xor_b32_e32 v155, 32, v194
	v_mov_b64_e32 v[184:185], s[38:39]
	v_cndmask_b32_e32 v149, v194, v149, vcc
	v_lshlrev_b32_e32 v149, 2, v149
	v_cmp_lt_i32_e32 vcc, v155, v151
	v_or_b32_e32 v158, s8, v186
	v_ashrrev_i32_e32 v159, 31, v158
	v_cndmask_b32_e32 v151, v194, v155, vcc
	v_lshlrev_b32_e32 v151, 2, v151
	s_waitcnt vmcnt(0)
	v_add_f32_e32 v196, v160, v161
	v_add_f32_e32 v197, v162, v163
	v_add_f32_e32 v164, v164, v165
	v_add_f32_e32 v166, v166, v167
	v_add_f32_e32 v172, v172, v173
	v_add_f32_e32 v174, v174, v175
	v_add_f32_e32 v176, v176, v177
	v_add_f32_e32 v178, v178, v179
	v_add_f32_e32 v161, v196, v197
	v_add_f32_e32 v160, v164, v166
	v_add_f32_e32 v163, v172, v174
	v_add_f32_e32 v162, v176, v178
	ds_bpermute_b32 v165, v149, v161
	ds_bpermute_b32 v164, v149, v160
	ds_bpermute_b32 v167, v149, v163
	ds_bpermute_b32 v166, v149, v162
	v_mul_f32_e32 v180, v239, v180
	v_mul_f32_e32 v181, v239, v181
	v_mul_f32_e32 v182, v239, v182
	v_mul_f32_e32 v183, v239, v183
	ds_write_b128 v193, v[180:183]
	s_waitcnt lgkmcnt(3)
	v_pk_add_f32 v[172:173], v[160:161], v[164:165]
	ds_bpermute_b32 v197, v151, v173
	s_waitcnt lgkmcnt(2)
	v_pk_add_f32 v[174:175], v[162:163], v[166:167]
	ds_bpermute_b32 v196, v151, v172
	ds_bpermute_b32 v199, v151, v175
	ds_bpermute_b32 v198, v151, v174
	ds_read_b128 v[160:163], v195
	ds_read_b128 v[164:167], v195 offset:256
	ds_read_b128 v[176:179], v195 offset:512
	ds_read_b128 v[180:183], v195 offset:768
	s_waitcnt lgkmcnt(6)
	v_pk_add_f32 v[172:173], v[172:173], v[196:197]
	s_nop 0
	v_pk_fma_f32 v[172:173], v[172:173], s[24:25], v[184:185] op_sel_hi:[1,0,0]
	s_waitcnt lgkmcnt(4)
	v_pk_add_f32 v[174:175], v[174:175], v[198:199]
	v_pk_fma_f32 v[174:175], v[174:175], s[24:25], v[184:185] op_sel_hi:[1,0,0]
	v_rsq_f32_e32 v155, v173
	v_rsq_f32_e32 v168, v175
	v_rsq_f32_e32 v173, v174
	v_rsq_f32_e32 v157, v172
	v_mov_b32_e32 v174, v155
	v_mov_b32_e32 v170, v168
	v_mov_b32_e32 v168, v173
	v_pk_mul_f32 v[124:125], v[124:125], v[174:175] op_sel_hi:[1,0]
	v_pk_mul_f32 v[112:113], v[112:113], v[168:169] op_sel_hi:[1,0]
	v_pk_mul_f32 v[116:117], v[116:117], v[170:171] op_sel_hi:[1,0]
	s_waitcnt lgkmcnt(0)
	v_pk_fma_f32 v[204:205], v[176:177], v[124:125], v[180:181]
	v_mov_b32_dpp v184, v112 row_shr:1 row_mask:0xf bank_mask:0xf bound_ctrl:1
	v_mov_b32_dpp v185, v113 row_shr:1 row_mask:0xf bank_mask:0xf bound_ctrl:1
	v_mov_b32_dpp v196, v116 row_shr:1 row_mask:0xf bank_mask:0xf bound_ctrl:1
	v_mov_b32_dpp v197, v117 row_shr:1 row_mask:0xf bank_mask:0xf bound_ctrl:1
	v_pk_fma_f32 v[204:205], v[164:165], v[184:185], v[204:205]
	v_pk_fma_f32 v[196:197], v[160:161], v[196:197], v[204:205]
	v_mov_b32_e32 v172, v157
	v_pk_mul_f32 v[126:127], v[126:127], v[174:175] op_sel_hi:[1,0]
	v_pk_mul_f32 v[120:121], v[120:121], v[172:173] op_sel_hi:[1,0]
	v_pk_mul_f32 v[114:115], v[114:115], v[168:169] op_sel_hi:[1,0]
	v_exp_f32_e32 v240, v196
	v_pk_mul_f32 v[118:119], v[118:119], v[170:171] op_sel_hi:[1,0]
	v_mov_b32_dpp v198, v114 row_shr:1 row_mask:0xf bank_mask:0xf bound_ctrl:1
	v_mov_b32_dpp v199, v115 row_shr:1 row_mask:0xf bank_mask:0xf bound_ctrl:1
	v_pk_fma_f32 v[202:203], v[178:179], v[126:127], v[182:183]
	v_pk_fma_f32 v[204:205], v[176:177], v[120:121], v[180:181]
	v_exp_f32_e32 v241, v197
	v_pk_mul_f32 v[122:123], v[122:123], v[172:173] op_sel_hi:[1,0]
	v_mov_b32_dpp v200, v118 row_shr:1 row_mask:0xf bank_mask:0xf bound_ctrl:1
	v_mov_b32_dpp v201, v119 row_shr:1 row_mask:0xf bank_mask:0xf bound_ctrl:1
	v_pk_fma_f32 v[202:203], v[166:167], v[198:199], v[202:203]
	v_pk_fma_f32 v[204:205], v[164:165], v[124:125], v[204:205]
	v_pk_fma_f32 v[200:201], v[162:163], v[200:201], v[202:203]
	v_pk_fma_f32 v[202:203], v[178:179], v[122:123], v[182:183]
	v_pk_fma_f32 v[184:185], v[160:161], v[184:185], v[204:205]
	v_pk_fma_f32 v[204:205], v[176:177], v[116:117], v[180:181]
	v_pk_fma_f32 v[176:177], v[176:177], v[112:113], v[180:181]
	v_pk_fma_f32 v[202:203], v[166:167], v[126:127], v[202:203]
	v_pk_fma_f32 v[204:205], v[164:165], v[120:121], v[204:205]
	v_pk_fma_f32 v[164:165], v[164:165], v[116:117], v[176:177]
	v_pk_fma_f32 v[198:199], v[162:163], v[198:199], v[202:203]
	v_pk_fma_f32 v[202:203], v[178:179], v[118:119], v[182:183]
	v_pk_fma_f32 v[204:205], v[160:161], v[124:125], v[204:205]
	v_pk_fma_f32 v[178:179], v[178:179], v[114:115], v[182:183]
	v_pk_fma_f32 v[214:215], v[160:161], v[120:121], v[164:165]
	v_pk_add_f32 v[240:241], v[240:241], v[250:251]
	v_rcp_f32_e32 v160, v240
	v_pk_fma_f32 v[202:203], v[166:167], v[122:123], v[202:203]
	v_pk_fma_f32 v[166:167], v[166:167], v[118:119], v[178:179]
	v_exp_f32_e32 v242, v200
	v_pk_fma_f32 v[202:203], v[162:163], v[126:127], v[202:203]
	v_pk_fma_f32 v[212:213], v[162:163], v[122:123], v[166:167]
	v_exp_f32_e32 v243, v201
	v_rcp_f32_e32 v161, v241
	v_pk_add_f32 v[242:243], v[242:243], v[250:251]
	v_rcp_f32_e32 v162, v242
	v_rcp_f32_e32 v163, v243
; #define PG8_LAS __attribute__((address_space(3)))
; __device__ __forceinline__ unsigned pk2(float a, float b) { return pg8::cvt_pk_bf16(a, b); }
; __device__ __forceinline__ float row_up1(float v) { return dpp_mov<0x111>(v); }
; __device__ __forceinline__ float siluf_(float x) { return x * __builtin_amdgcn_rcpf(1.0f + __builtin_amdgcn_exp2f(x * -1.4426950408889634f)); }
;     __device__ __forceinline__ void operator()(f32x4 (&acc)[2][2][4][2], const pg8::Unit& u, int wr, int wc, int fr, int fq) const {
;     ...
;                     g[0] = bb + w2 * x0 + w1 * p1 + w0 * p2; g[1] = bb + w2 * x1 + w1 * x0 + w0 * p1;
;                     g[2] = bb + w2 * x2 + w1 * x1 + w0 * x0; g[3] = bb + w2 * x3 + w1 * x2 + w0 * x1;
; #pragma unroll
;                     for (int m = 0; m < 4; ++m)
; #pragma unroll
;                         for (int c = 0; c < 4; ++c) g[m][c] = siluf_(g[m][c]);
;                 }
;                 __builtin_amdgcn_sched_barrier(0);
;                 {   const PG8_LAS unsigned char* wq = wl + 128 + (8 * fq + 4 * n) * 4;
;                     const f32x4 w0 = *(const PG8_LAS f32x4*)(wq), w1 = *(const PG8_LAS f32x4*)(wq + 256), w2 = *(const PG8_LAS f32x4*)(wq + 512), bb = *(const PG8_LAS f32x4*)(wq + 768);
;                     const f32x4 x0 = acc[ai][1][0][n] * rstd[0], x1 = acc[ai][1][1][n] * rstd[1], x2 = acc[ai][1][2][n] * rstd[2], x3 = acc[ai][1][3][n] * rstd[3];
;                     acc[ai][1][0][n] = x0; acc[ai][1][1][n] = x1; acc[ai][1][2][n] = x2; acc[ai][1][3][n] = x3;
;                     f32x4 p1, p2;
; #pragma unroll
;                     for (int c = 0; c < 4; ++c) { p1[c] = row_up1(x3[c]); p2[c] = row_up1(x2[c]); }
;                     g[0] *= bb + w2 * x0 + w1 * p1 + w0 * p2; g[1] *= bb + w2 * x1 + w1 * x0 + w0 * p1;
;                     g[2] *= bb + w2 * x2 + w1 * x1 + w0 * x0; g[3] *= bb + w2 * x3 + w1 * x2 + w0 * x1;
;                 }
; #pragma unroll
;                 for (int m = 0; m < 4; ++m) { pk[n][m].x = pk2(g[m][0], g[m][1]); pk[n][m].y = pk2(g[m][2], g[m][3]); }
	v_exp_f32_e32 v244, v184
	v_exp_f32_e32 v245, v185
	v_pk_mul_f32 v[216:217], v[196:197], v[160:161]
	v_pk_add_f32 v[244:245], v[244:245], v[250:251]
	v_rcp_f32_e32 v160, v244
	v_exp_f32_e32 v246, v198
	v_pk_mul_f32 v[218:219], v[200:201], v[162:163]
	v_exp_f32_e32 v247, v199
	v_rcp_f32_e32 v161, v245
	v_pk_add_f32 v[246:247], v[246:247], v[250:251]
	v_rcp_f32_e32 v162, v246
	v_rcp_f32_e32 v163, v247
	v_exp_f32_e32 v248, v204
	v_exp_f32_e32 v249, v205
	v_pk_mul_f32 v[184:185], v[184:185], v[160:161]
	v_pk_add_f32 v[248:249], v[248:249], v[250:251]
	v_rcp_f32_e32 v160, v248
	v_exp_f32_e32 v240, v202
	v_exp_f32_e32 v241, v203
	v_rcp_f32_e32 v161, v249
	v_pk_add_f32 v[240:241], v[240:241], v[250:251]
	v_rcp_f32_e32 v164, v240
	v_exp_f32_e32 v242, v214
	v_exp_f32_e32 v243, v215
	v_rcp_f32_e32 v165, v241
	v_pk_add_f32 v[242:243], v[242:243], v[250:251]
	v_rcp_f32_e32 v220, v242
	v_exp_f32_e32 v244, v212
	v_exp_f32_e32 v245, v213
	v_rcp_f32_e32 v221, v243
	v_pk_add_f32 v[244:245], v[244:245], v[250:251]
	v_rcp_f32_e32 v222, v244
	v_rcp_f32_e32 v223, v245
	v_pk_mul_f32 v[224:225], v[198:199], v[162:163]
	v_pk_mul_f32 v[226:227], v[204:205], v[160:161]
	v_pk_mul_f32 v[228:229], v[202:203], v[164:165]
	ds_read_b128 v[196:199], v195 offset:128
	ds_read_b128 v[200:203], v195 offset:384
	ds_read_b128 v[204:207], v195 offset:640
	ds_read_b128 v[208:211], v195 offset:896
	v_pk_mul_f32 v[176:177], v[108:109], v[174:175] op_sel_hi:[1,0]
	v_pk_mul_f32 v[164:165], v[96:97], v[168:169] op_sel_hi:[1,0]
	v_pk_mul_f32 v[180:181], v[100:101], v[170:171] op_sel_hi:[1,0]
	v_pk_mul_f32 v[160:161], v[104:105], v[172:173] op_sel_hi:[1,0]
	v_mov_b32_dpp v96, v164 row_shr:1 row_mask:0xf bank_mask:0xf bound_ctrl:1
	v_mov_b32_dpp v97, v165 row_shr:1 row_mask:0xf bank_mask:0xf bound_ctrl:1
	s_waitcnt lgkmcnt(0)
	v_pk_fma_f32 v[108:109], v[176:177], v[204:205], v[208:209]
	v_pk_mul_f32 v[166:167], v[98:99], v[168:169] op_sel_hi:[1,0]
	v_mov_b32_dpp v98, v180 row_shr:1 row_mask:0xf bank_mask:0xf bound_ctrl:1
	v_mov_b32_dpp v99, v181 row_shr:1 row_mask:0xf bank_mask:0xf bound_ctrl:1
	v_pk_fma_f32 v[108:109], v[200:201], v[96:97], v[108:109]
	v_pk_mul_f32 v[178:179], v[110:111], v[174:175] op_sel_hi:[1,0]
	v_pk_fma_f32 v[98:99], v[196:197], v[98:99], v[108:109]
	v_pk_fma_f32 v[108:109], v[160:161], v[204:205], v[208:209]
	v_pk_mul_f32 v[182:183], v[102:103], v[170:171] op_sel_hi:[1,0]
	v_mov_b32_dpp v100, v166 row_shr:1 row_mask:0xf bank_mask:0xf bound_ctrl:1
	v_mov_b32_dpp v101, v167 row_shr:1 row_mask:0xf bank_mask:0xf bound_ctrl:1
	v_pk_fma_f32 v[110:111], v[178:179], v[206:207], v[210:211]
	v_pk_fma_f32 v[108:109], v[176:177], v[200:201], v[108:109]
	v_pk_mul_f32 v[162:163], v[106:107], v[172:173] op_sel_hi:[1,0]
	v_mov_b32_dpp v102, v182 row_shr:1 row_mask:0xf bank_mask:0xf bound_ctrl:1
	v_mov_b32_dpp v103, v183 row_shr:1 row_mask:0xf bank_mask:0xf bound_ctrl:1
	v_pk_fma_f32 v[110:111], v[202:203], v[100:101], v[110:111]
	v_pk_fma_f32 v[96:97], v[196:197], v[96:97], v[108:109]
	v_pk_fma_f32 v[108:109], v[180:181], v[204:205], v[208:209]
	v_pk_fma_f32 v[102:103], v[198:199], v[102:103], v[110:111]
	v_pk_fma_f32 v[110:111], v[162:163], v[206:207], v[210:211]
	v_pk_fma_f32 v[108:109], v[160:161], v[200:201], v[108:109]
	v_pk_fma_f32 v[110:111], v[178:179], v[202:203], v[110:111]
	v_pk_fma_f32 v[108:109], v[176:177], v[196:197], v[108:109]
	v_pk_fma_f32 v[100:101], v[198:199], v[100:101], v[110:111]
	v_pk_mul_f32 v[96:97], v[184:185], v[96:97]
	v_pk_fma_f32 v[110:111], v[182:183], v[206:207], v[210:211]
	v_pk_mul_f32 v[184:185], v[108:109], v[226:227]
	v_pk_fma_f32 v[108:109], v[164:165], v[204:205], v[208:209]
	v_pk_fma_f32 v[204:205], v[166:167], v[206:207], v[210:211]
	v_pk_fma_f32 v[110:111], v[162:163], v[202:203], v[110:111]
	v_pk_fma_f32 v[202:203], v[182:183], v[202:203], v[204:205]
	v_pk_fma_f32 v[108:109], v[180:181], v[200:201], v[108:109]
	v_pk_mul_f32 v[106:107], v[212:213], v[222:223]
	v_pk_fma_f32 v[110:111], v[178:179], v[198:199], v[110:111]
	v_pk_fma_f32 v[108:109], v[160:161], v[196:197], v[108:109]
	v_pk_fma_f32 v[196:197], v[162:163], v[198:199], v[202:203]
	v_pk_mul_f32 v[104:105], v[214:215], v[220:221]
	v_pk_mul_f32 v[102:103], v[218:219], v[102:103]
	v_pk_mul_f32 v[98:99], v[216:217], v[98:99]
	v_pk_mul_f32 v[100:101], v[224:225], v[100:101]
	v_pk_mul_f32 v[110:111], v[110:111], v[228:229]
	v_pk_mul_f32 v[106:107], v[196:197], v[106:107]
	v_pk_mul_f32 v[196:197], v[108:109], v[104:105]
	v_cvt_pk_bf16_f32 v108, v98, v99
	v_cvt_pk_bf16_f32 v109, v102, v103
	v_cvt_pk_bf16_f32 v104, v96, v97
	v_cvt_pk_bf16_f32 v105, v100, v101
	v_cvt_pk_bf16_f32 v100, v184, v185
	v_cvt_pk_bf16_f32 v101, v110, v111
	s_nop 0
	v_cvt_pk_bf16_f32 v96, v196, v197
	v_cvt_pk_bf16_f32 v97, v106, v107
	ds_read_b128 v[196:199], v195 offset:16
	ds_read_b128 v[200:203], v195 offset:272
	ds_read_b128 v[204:207], v195 offset:528
	ds_read_b128 v[208:211], v195 offset:784
	v_pk_mul_f32 v[92:93], v[92:93], v[174:175] op_sel_hi:[1,0]
	v_pk_mul_f32 v[84:85], v[84:85], v[168:169] op_sel_hi:[1,0]
	v_pk_mul_f32 v[88:89], v[88:89], v[170:171] op_sel_hi:[1,0]
	v_pk_mul_f32 v[80:81], v[80:81], v[172:173] op_sel_hi:[1,0]
	v_mov_b32_dpp v98, v84 row_shr:1 row_mask:0xf bank_mask:0xf bound_ctrl:1
	v_mov_b32_dpp v99, v85 row_shr:1 row_mask:0xf bank_mask:0xf bound_ctrl:1
	s_waitcnt lgkmcnt(0)
; #define PG8_LAS __attribute__((address_space(3)))
; __device__ __forceinline__ float row_up1(float v) { return dpp_mov<0x111>(v); }
; __device__ __forceinline__ float siluf_(float x) { return x * __builtin_amdgcn_rcpf(1.0f + __builtin_amdgcn_exp2f(x * -1.4426950408889634f)); }
;     __device__ __forceinline__ void operator()(f32x4 (&acc)[2][2][4][2], const pg8::Unit& u, int wr, int wc, int fr, int fq) const {
;     ...
;                 {   const PG8_LAS unsigned char* wq = wl + (8 * fq + 4 * n) * 4;
;                     const f32x4 w0 = *(const PG8_LAS f32x4*)(wq), w1 = *(const PG8_LAS f32x4*)(wq + 256), w2 = *(const PG8_LAS f32x4*)(wq + 512), bb = *(const PG8_LAS f32x4*)(wq + 768);
;                     const f32x4 x0 = acc[ai][0][0][n] * rstd[0], x1 = acc[ai][0][1][n] * rstd[1], x2 = acc[ai][0][2][n] * rstd[2], x3 = acc[ai][0][3][n] * rstd[3];
;                     acc[ai][0][0][n] = x0; acc[ai][0][1][n] = x1; acc[ai][0][2][n] = x2; acc[ai][0][3][n] = x3;
;                     f32x4 p1, p2;
; #pragma unroll
;                     for (int c = 0; c < 4; ++c) { p1[c] = row_up1(x3[c]); p2[c] = row_up1(x2[c]); }
;                     g[0] = bb + w2 * x0 + w1 * p1 + w0 * p2; g[1] = bb + w2 * x1 + w1 * x0 + w0 * p1;
;                     g[2] = bb + w2 * x2 + w1 * x1 + w0 * x0; g[3] = bb + w2 * x3 + w1 * x2 + w0 * x1;
; #pragma unroll
;                     for (int m = 0; m < 4; ++m)
; #pragma unroll
;                         for (int c = 0; c < 4; ++c) g[m][c] = siluf_(g[m][c]);
;                 }
;                 __builtin_amdgcn_sched_barrier(0);
;                 {   const PG8_LAS unsigned char* wq = wl + 128 + (8 * fq + 4 * n) * 4;
;                     const f32x4 w0 = *(const PG8_LAS f32x4*)(wq), w1 = *(const PG8_LAS f32x4*)(wq + 256), w2 = *(const PG8_LAS f32x4*)(wq + 512), bb = *(const PG8_LAS f32x4*)(wq + 768);
	v_pk_fma_f32 v[212:213], v[92:93], v[204:205], v[208:209]
	v_mov_b32_dpp v102, v88 row_shr:1 row_mask:0xf bank_mask:0xf bound_ctrl:1
	v_mov_b32_dpp v103, v89 row_shr:1 row_mask:0xf bank_mask:0xf bound_ctrl:1
	v_pk_fma_f32 v[212:213], v[200:201], v[98:99], v[212:213]
	v_pk_mul_f32 v[94:95], v[94:95], v[174:175] op_sel_hi:[1,0]
	v_pk_fma_f32 v[102:103], v[196:197], v[102:103], v[212:213]
	v_pk_mul_f32 v[86:87], v[86:87], v[168:169] op_sel_hi:[1,0]
	v_exp_f32_e32 v246, v102
	v_pk_fma_f32 v[212:213], v[80:81], v[204:205], v[208:209]
	v_exp_f32_e32 v247, v103
	v_pk_mul_f32 v[90:91], v[90:91], v[170:171] op_sel_hi:[1,0]
	v_mov_b32_dpp v106, v86 row_shr:1 row_mask:0xf bank_mask:0xf bound_ctrl:1
	v_mov_b32_dpp v107, v87 row_shr:1 row_mask:0xf bank_mask:0xf bound_ctrl:1
	v_pk_fma_f32 v[184:185], v[94:95], v[206:207], v[210:211]
	v_pk_fma_f32 v[212:213], v[92:93], v[200:201], v[212:213]
	v_mov_b32_dpp v110, v90 row_shr:1 row_mask:0xf bank_mask:0xf bound_ctrl:1
	v_mov_b32_dpp v111, v91 row_shr:1 row_mask:0xf bank_mask:0xf bound_ctrl:1
	v_pk_fma_f32 v[184:185], v[202:203], v[106:107], v[184:185]
	v_pk_fma_f32 v[98:99], v[196:197], v[98:99], v[212:213]
	v_pk_fma_f32 v[212:213], v[88:89], v[204:205], v[208:209]
	v_pk_fma_f32 v[204:205], v[84:85], v[204:205], v[208:209]
	v_pk_fma_f32 v[110:111], v[198:199], v[110:111], v[184:185]
	v_pk_fma_f32 v[212:213], v[80:81], v[200:201], v[212:213]
	v_pk_fma_f32 v[200:201], v[88:89], v[200:201], v[204:205]
	v_pk_fma_f32 v[212:213], v[92:93], v[196:197], v[212:213]
	v_pk_fma_f32 v[216:217], v[80:81], v[196:197], v[200:201]
	v_pk_add_f32 v[246:247], v[246:247], v[250:251]
	v_rcp_f32_e32 v196, v246
	v_pk_mul_f32 v[82:83], v[82:83], v[172:173] op_sel_hi:[1,0]
	v_exp_f32_e32 v248, v110
	v_pk_fma_f32 v[184:185], v[82:83], v[206:207], v[210:211]
	v_exp_f32_e32 v249, v111
	v_pk_fma_f32 v[184:185], v[94:95], v[202:203], v[184:185]
	v_rcp_f32_e32 v197, v247
	v_pk_fma_f32 v[106:107], v[198:199], v[106:107], v[184:185]
	v_pk_fma_f32 v[184:185], v[90:91], v[206:207], v[210:211]
	v_pk_fma_f32 v[206:207], v[86:87], v[206:207], v[210:211]
	v_pk_fma_f32 v[184:185], v[82:83], v[202:203], v[184:185]
	v_pk_fma_f32 v[202:203], v[90:91], v[202:203], v[206:207]
	v_pk_fma_f32 v[184:185], v[94:95], v[198:199], v[184:185]
	v_pk_fma_f32 v[214:215], v[82:83], v[198:199], v[202:203]
	v_pk_add_f32 v[248:249], v[248:249], v[250:251]
	v_rcp_f32_e32 v198, v248
	v_rcp_f32_e32 v199, v249
	v_exp_f32_e32 v240, v98
	v_exp_f32_e32 v241, v99
	v_pk_mul_f32 v[102:103], v[102:103], v[196:197]
	v_pk_add_f32 v[240:241], v[240:241], v[250:251]
	v_rcp_f32_e32 v196, v240
	v_exp_f32_e32 v242, v106
	v_exp_f32_e32 v243, v107
	v_rcp_f32_e32 v197, v241
	v_pk_mul_f32 v[110:111], v[110:111], v[198:199]
	v_pk_add_f32 v[242:243], v[242:243], v[250:251]
	v_rcp_f32_e32 v198, v242
	v_rcp_f32_e32 v199, v243
	v_exp_f32_e32 v244, v212
	v_exp_f32_e32 v245, v213
	v_pk_mul_f32 v[98:99], v[98:99], v[196:197]
	v_pk_add_f32 v[244:245], v[244:245], v[250:251]
	v_rcp_f32_e32 v196, v244
	v_exp_f32_e32 v246, v184
	v_exp_f32_e32 v247, v185
	v_rcp_f32_e32 v197, v245
	v_pk_add_f32 v[246:247], v[246:247], v[250:251]
	v_rcp_f32_e32 v200, v246
	v_exp_f32_e32 v248, v216
	v_exp_f32_e32 v249, v217
	v_rcp_f32_e32 v201, v247
	v_pk_add_f32 v[248:249], v[248:249], v[250:251]
	v_rcp_f32_e32 v218, v248
	v_exp_f32_e32 v240, v214
	v_exp_f32_e32 v241, v215
	v_rcp_f32_e32 v219, v249
	v_pk_add_f32 v[240:241], v[240:241], v[250:251]
	v_rcp_f32_e32 v220, v240
	v_pk_mul_f32 v[106:107], v[106:107], v[198:199]
	v_rcp_f32_e32 v221, v241
	v_pk_mul_f32 v[212:213], v[212:213], v[196:197]
	v_pk_mul_f32 v[222:223], v[184:185], v[200:201]
	ds_read_b128 v[196:199], v195 offset:144
	ds_read_b128 v[200:203], v195 offset:400
	ds_read_b128 v[204:207], v195 offset:656
	ds_read_b128 v[208:211], v195 offset:912
	v_pk_mul_f32 v[184:185], v[66:67], v[174:175] op_sel_hi:[1,0]
	v_pk_mul_f32 v[174:175], v[64:65], v[174:175] op_sel_hi:[1,0]
	v_pk_mul_f32 v[66:67], v[68:69], v[172:173] op_sel_hi:[1,0]
	v_pk_mul_f32 v[68:69], v[76:77], v[168:169] op_sel_hi:[1,0]
	v_pk_mul_f32 v[70:71], v[70:71], v[172:173] op_sel_hi:[1,0]
	v_pk_mul_f32 v[172:173], v[74:75], v[170:171] op_sel_hi:[1,0]
	v_pk_mul_f32 v[74:75], v[72:73], v[170:171] op_sel_hi:[1,0]
	v_mov_b32_dpp v64, v68 row_shr:1 row_mask:0xf bank_mask:0xf bound_ctrl:1
	v_mov_b32_dpp v65, v69 row_shr:1 row_mask:0xf bank_mask:0xf bound_ctrl:1
	v_pk_mul_f32 v[216:217], v[216:217], v[218:219]
	s_waitcnt lgkmcnt(0)
; #define PG8_LAS __attribute__((address_space(3)))
; __device__ __forceinline__ unsigned pk2(float a, float b) { return pg8::cvt_pk_bf16(a, b); }
; __device__ __forceinline__ float row_up1(float v) { return dpp_mov<0x111>(v); }
;     __device__ __forceinline__ void operator()(f32x4 (&acc)[2][2][4][2], const pg8::Unit& u, int wr, int wc, int fr, int fq) const {
;     ...
;                 {   const PG8_LAS unsigned char* wq = wl + 128 + (8 * fq + 4 * n) * 4;
;                     const f32x4 w0 = *(const PG8_LAS f32x4*)(wq), w1 = *(const PG8_LAS f32x4*)(wq + 256), w2 = *(const PG8_LAS f32x4*)(wq + 512), bb = *(const PG8_LAS f32x4*)(wq + 768);
;                     const f32x4 x0 = acc[ai][1][0][n] * rstd[0], x1 = acc[ai][1][1][n] * rstd[1], x2 = acc[ai][1][2][n] * rstd[2], x3 = acc[ai][1][3][n] * rstd[3];
;                     acc[ai][1][0][n] = x0; acc[ai][1][1][n] = x1; acc[ai][1][2][n] = x2; acc[ai][1][3][n] = x3;
;                     f32x4 p1, p2;
; #pragma unroll
;                     for (int c = 0; c < 4; ++c) { p1[c] = row_up1(x3[c]); p2[c] = row_up1(x2[c]); }
;                     g[0] *= bb + w2 * x0 + w1 * p1 + w0 * p2; g[1] *= bb + w2 * x1 + w1 * x0 + w0 * p1;
;                     g[2] *= bb + w2 * x2 + w1 * x1 + w0 * x0; g[3] *= bb + w2 * x3 + w1 * x2 + w0 * x1;
;                 }
; #pragma unroll
;                 for (int m = 0; m < 4; ++m) { pk[n][m].x = pk2(g[m][0], g[m][1]); pk[n][m].y = pk2(g[m][2], g[m][3]); }
;                 __builtin_amdgcn_sched_barrier(0);
;             }
; #pragma unroll
;             for (int m = 0; m < 4; ++m) if (fr != 0 || m >= 2) {
;                 u32x4 w; w.x = pk[0][m].x; w.y = pk[0][m].y; w.z = pk[1][m].x; w.w = pk[1][m].y;
;                 *(u32x4*)(ACT + (size_t)(tb + m) * DFF + colj) = w; }
	v_pk_fma_f32 v[218:219], v[174:175], v[204:205], v[208:209]
	v_pk_mul_f32 v[72:73], v[78:79], v[168:169] op_sel_hi:[1,0]
	v_mov_b32_dpp v76, v74 row_shr:1 row_mask:0xf bank_mask:0xf bound_ctrl:1
	v_mov_b32_dpp v77, v75 row_shr:1 row_mask:0xf bank_mask:0xf bound_ctrl:1
	v_pk_fma_f32 v[218:219], v[200:201], v[64:65], v[218:219]
	v_mov_b32_dpp v78, v72 row_shr:1 row_mask:0xf bank_mask:0xf bound_ctrl:1
	v_mov_b32_dpp v79, v73 row_shr:1 row_mask:0xf bank_mask:0xf bound_ctrl:1
	v_pk_mul_f32 v[214:215], v[214:215], v[220:221]
	v_pk_fma_f32 v[220:221], v[184:185], v[206:207], v[210:211]
	v_pk_fma_f32 v[76:77], v[196:197], v[76:77], v[218:219]
	v_mov_b32_dpp v224, v172 row_shr:1 row_mask:0xf bank_mask:0xf bound_ctrl:1
	v_mov_b32_dpp v225, v173 row_shr:1 row_mask:0xf bank_mask:0xf bound_ctrl:1
	v_pk_fma_f32 v[220:221], v[202:203], v[78:79], v[220:221]
	v_pk_mul_f32 v[76:77], v[102:103], v[76:77]
	v_pk_fma_f32 v[102:103], v[66:67], v[204:205], v[208:209]
	v_pk_fma_f32 v[218:219], v[198:199], v[224:225], v[220:221]
	v_pk_fma_f32 v[102:103], v[174:175], v[200:201], v[102:103]
	v_pk_mul_f32 v[218:219], v[110:111], v[218:219]
	v_pk_fma_f32 v[110:111], v[70:71], v[206:207], v[210:211]
	v_pk_fma_f32 v[64:65], v[196:197], v[64:65], v[102:103]
	v_pk_fma_f32 v[102:103], v[172:173], v[206:207], v[210:211]
	v_pk_fma_f32 v[110:111], v[184:185], v[202:203], v[110:111]
	v_pk_fma_f32 v[102:103], v[70:71], v[202:203], v[102:103]
	v_pk_fma_f32 v[78:79], v[198:199], v[78:79], v[110:111]
	v_pk_mul_f32 v[64:65], v[98:99], v[64:65]
	v_pk_fma_f32 v[98:99], v[74:75], v[204:205], v[208:209]
	v_pk_fma_f32 v[102:103], v[184:185], v[198:199], v[102:103]
	v_pk_mul_f32 v[78:79], v[106:107], v[78:79]
	v_pk_fma_f32 v[98:99], v[66:67], v[200:201], v[98:99]
	v_pk_mul_f32 v[220:221], v[222:223], v[102:103]
	v_pk_fma_f32 v[102:103], v[68:69], v[204:205], v[208:209]
	v_pk_fma_f32 v[106:107], v[72:73], v[206:207], v[210:211]
	v_pk_fma_f32 v[98:99], v[174:175], v[196:197], v[98:99]
	v_pk_fma_f32 v[106:107], v[172:173], v[202:203], v[106:107]
	v_pk_fma_f32 v[102:103], v[74:75], v[200:201], v[102:103]
	v_pk_mul_f32 v[98:99], v[212:213], v[98:99]
	v_pk_fma_f32 v[102:103], v[66:67], v[196:197], v[102:103]
	v_pk_fma_f32 v[106:107], v[70:71], v[198:199], v[106:107]
	v_pk_mul_f32 v[198:199], v[216:217], v[102:103]
	v_pk_mul_f32 v[196:197], v[214:215], v[106:107]
	v_cvt_pk_bf16_f32 v110, v76, v77
	v_cvt_pk_bf16_f32 v111, v218, v219
	v_cvt_pk_bf16_f32 v106, v64, v65
	v_cvt_pk_bf16_f32 v107, v78, v79
	v_cvt_pk_bf16_f32 v102, v98, v99
	v_cvt_pk_bf16_f32 v103, v220, v221
	v_cvt_pk_bf16_f32 v98, v198, v199
	s_nop 0
	v_cvt_pk_bf16_f32 v99, v196, v197
	v_lshlrev_b64 v[64:65], 1, v[158:159]
	s_and_saveexec_b64 s[8:9], s[0:1]
	s_cbranch_execz .LBB0_750
	v_mov_b64_e32 v[76:77], s[22:23]
	v_mad_i64_i32 v[78:79], s[10:11], v148, s56, v[76:77]
	v_mad_i64_i32 v[76:77], s[10:11], v150, s56, v[76:77]
	v_lshl_add_u64 v[78:79], v[78:79], 0, v[64:65]
	v_lshl_add_u64 v[76:77], v[76:77], 0, v[64:65]
	global_store_dwordx4 v[78:79], v[108:111], off
	global_store_dwordx4 v[76:77], v[104:107], off

; #define PG8_LAS __attribute__((address_space(3)))
; __device__ __forceinline__ float row_up1(float v) { return dpp_mov<0x111>(v); }
; __device__ __forceinline__ float siluf_(float x) { return x * __builtin_amdgcn_rcpf(1.0f + __builtin_amdgcn_exp2f(x * -1.4426950408889634f)); }
;     __device__ __forceinline__ void operator()(f32x4 (&acc)[2][2][4][2], const pg8::Unit& u, int wr, int wc, int fr, int fq) const {
;     ...
;         for (int ai = 0; ai < 2; ++ai) {
;             const int tb = u.pm * 256 + ai * 128 + wr * 64 + 4 * fr;
;             float rstd[4];
; #pragma unroll
;             for (int m = 0; m < 4; ++m) { const f32x4 sv = *(const f32x4*)(SS + (size_t)(tb + m) * 16 + 4 * fq); float s = (sv[0] + sv[1]) + (sv[2] + sv[3]); s += __shfl_xor(s, 16); s += __shfl_xor(s, 32);
;                 rstd[m] = rsqrtf(s * (1.0f / 1024.0f) + EPS); }
;             u32x2 pk[2][4];
; #pragma unroll
;             for (int n = 0; n < 2; ++n) {
;                 f32x4 g[4];
;                 {   const PG8_LAS unsigned char* wq = wl + (8 * fq + 4 * n) * 4;
;                     const f32x4 w0 = *(const PG8_LAS f32x4*)(wq), w1 = *(const PG8_LAS f32x4*)(wq + 256), w2 = *(const PG8_LAS f32x4*)(wq + 512), bb = *(const PG8_LAS f32x4*)(wq + 768);
;                     const f32x4 x0 = acc[ai][0][0][n] * rstd[0], x1 = acc[ai][0][1][n] * rstd[1], x2 = acc[ai][0][2][n] * rstd[2], x3 = acc[ai][0][3][n] * rstd[3];
;                     acc[ai][0][0][n] = x0; acc[ai][0][1][n] = x1; acc[ai][0][2][n] = x2; acc[ai][0][3][n] = x3;
;                     f32x4 p1, p2;
; #pragma unroll
;                     for (int c = 0; c < 4; ++c) { p1[c] = row_up1(x3[c]); p2[c] = row_up1(x2[c]); }
;                     g[0] = bb + w2 * x0 + w1 * p1 + w0 * p2; g[1] = bb + w2 * x1 + w1 * x0 + w0 * p1;
;                     g[2] = bb + w2 * x2 + w1 * x1 + w0 * x0; g[3] = bb + w2 * x3 + w1 * x2 + w0 * x1;
; #pragma unroll
;                     for (int m = 0; m < 4; ++m)
; #pragma unroll
;                         for (int c = 0; c < 4; ++c) g[m][c] = siluf_(g[m][c]);
.LBB0_754:
	s_or_b64 exec, exec, s[8:9]
	s_nop 0
	v_add_u32_e32 v66, 0x80, v148
	v_ashrrev_i32_e32 v67, 31, v66
	v_lshlrev_b64 v[68:69], 6, v[66:67]
	v_lshl_add_u64 v[246:247], v[138:139], 0, v[68:69]
	v_add_u32_e32 v68, 0x81, v148
	global_load_dwordx4 v[74:77], v[246:247], off
	global_load_dwordx4 v[78:81], v[246:247], off offset:64
	v_add_u32_e32 v70, 0x82, v148
	global_load_dwordx4 v[82:85], v[246:247], off offset:128
	v_add_u32_e32 v72, 0x83, v148
	global_load_dwordx4 v[86:89], v[246:247], off offset:192
	s_waitcnt vmcnt(3)
	v_add_f32_e32 v90, v74, v75
	v_add_f32_e32 v91, v76, v77
	s_waitcnt vmcnt(2)
	v_add_f32_e32 v78, v78, v79
	v_add_f32_e32 v80, v80, v81
	s_waitcnt vmcnt(1)
	v_add_f32_e32 v82, v82, v83
	v_add_f32_e32 v84, v84, v85
	s_waitcnt vmcnt(0)
	v_add_f32_e32 v86, v86, v87
	v_add_f32_e32 v88, v88, v89
	v_add_f32_e32 v75, v90, v91
	v_add_f32_e32 v74, v78, v80
	v_add_f32_e32 v77, v82, v84
	v_add_f32_e32 v76, v86, v88
	ds_bpermute_b32 v79, v149, v75
	ds_bpermute_b32 v78, v149, v74
	ds_bpermute_b32 v81, v149, v77
	ds_bpermute_b32 v80, v149, v76
	v_mov_b64_e32 v[82:83], s[38:39]
	s_waitcnt lgkmcnt(2)
	v_pk_add_f32 v[84:85], v[74:75], v[78:79]
	ds_bpermute_b32 v89, v151, v85
	s_waitcnt lgkmcnt(1)
	v_pk_add_f32 v[86:87], v[76:77], v[80:81]
	ds_bpermute_b32 v88, v151, v84
	ds_bpermute_b32 v99, v151, v87
	ds_bpermute_b32 v98, v151, v86
	ds_read_b128 v[74:77], v195
	ds_read_b128 v[78:81], v195 offset:256
	ds_read_b128 v[90:93], v195 offset:512
	ds_read_b128 v[94:97], v195 offset:768
	s_waitcnt lgkmcnt(6)
	v_pk_add_f32 v[84:85], v[84:85], v[88:89]
	s_nop 0
	v_pk_fma_f32 v[84:85], v[84:85], s[24:25], v[82:83] op_sel_hi:[1,0,0]
	s_waitcnt lgkmcnt(4)
	v_pk_add_f32 v[86:87], v[86:87], v[98:99]
	v_pk_fma_f32 v[82:83], v[86:87], s[24:25], v[82:83] op_sel_hi:[1,0,0]
	v_rsq_f32_e32 v67, v85
	v_rsq_f32_e32 v73, v82
	v_rsq_f32_e32 v69, v84
	v_rsq_f32_e32 v71, v83
	v_mov_b32_e32 v88, v67
	v_mov_b32_e32 v82, v73
	v_mov_b32_e32 v84, v71
	v_pk_mul_f32 v[60:61], v[60:61], v[88:89] op_sel_hi:[1,0]
	v_pk_mul_f32 v[48:49], v[48:49], v[82:83] op_sel_hi:[1,0]
	v_pk_mul_f32 v[52:53], v[52:53], v[84:85] op_sel_hi:[1,0]
	s_waitcnt lgkmcnt(0)
	v_pk_fma_f32 v[108:109], v[90:91], v[60:61], v[94:95]
	v_mov_b32_dpp v98, v48 row_shr:1 row_mask:0xf bank_mask:0xf bound_ctrl:1
	v_mov_b32_dpp v99, v49 row_shr:1 row_mask:0xf bank_mask:0xf bound_ctrl:1
	v_mov_b32_dpp v100, v52 row_shr:1 row_mask:0xf bank_mask:0xf bound_ctrl:1
	v_mov_b32_dpp v101, v53 row_shr:1 row_mask:0xf bank_mask:0xf bound_ctrl:1
	v_pk_fma_f32 v[108:109], v[78:79], v[98:99], v[108:109]
	v_mov_b32_e32 v86, v69
	v_pk_fma_f32 v[100:101], v[74:75], v[100:101], v[108:109]
	v_pk_mul_f32 v[62:63], v[62:63], v[88:89] op_sel_hi:[1,0]
	v_exp_f32_e32 v242, v100
	v_pk_mul_f32 v[50:51], v[50:51], v[82:83] op_sel_hi:[1,0]
	v_exp_f32_e32 v243, v101
	v_pk_mul_f32 v[56:57], v[56:57], v[86:87] op_sel_hi:[1,0]
	v_pk_mul_f32 v[54:55], v[54:55], v[84:85] op_sel_hi:[1,0]
	v_mov_b32_dpp v102, v50 row_shr:1 row_mask:0xf bank_mask:0xf bound_ctrl:1
	v_mov_b32_dpp v103, v51 row_shr:1 row_mask:0xf bank_mask:0xf bound_ctrl:1
	v_pk_fma_f32 v[106:107], v[92:93], v[62:63], v[96:97]
	v_mov_b32_dpp v104, v54 row_shr:1 row_mask:0xf bank_mask:0xf bound_ctrl:1
	v_mov_b32_dpp v105, v55 row_shr:1 row_mask:0xf bank_mask:0xf bound_ctrl:1
	v_pk_fma_f32 v[112:113], v[90:91], v[56:57], v[94:95]
	v_pk_fma_f32 v[106:107], v[80:81], v[102:103], v[106:107]
	v_pk_fma_f32 v[108:109], v[90:91], v[52:53], v[94:95]
	v_pk_fma_f32 v[90:91], v[90:91], v[48:49], v[94:95]
	v_pk_fma_f32 v[112:113], v[78:79], v[60:61], v[112:113]
	v_pk_fma_f32 v[104:105], v[76:77], v[104:105], v[106:107]
	v_pk_fma_f32 v[108:109], v[78:79], v[56:57], v[108:109]
	v_pk_fma_f32 v[78:79], v[78:79], v[52:53], v[90:91]
	v_pk_fma_f32 v[98:99], v[74:75], v[98:99], v[112:113]
	v_pk_fma_f32 v[108:109], v[74:75], v[60:61], v[108:109]
	v_pk_fma_f32 v[116:117], v[74:75], v[56:57], v[78:79]
	v_pk_add_f32 v[242:243], v[242:243], v[250:251]
	v_rcp_f32_e32 v74, v242
	v_exp_f32_e32 v244, v104
	v_exp_f32_e32 v245, v105
	v_pk_mul_f32 v[58:59], v[58:59], v[86:87] op_sel_hi:[1,0]
	v_pk_fma_f32 v[106:107], v[92:93], v[54:55], v[96:97]
	v_pk_fma_f32 v[110:111], v[92:93], v[58:59], v[96:97]
	v_pk_fma_f32 v[92:93], v[92:93], v[50:51], v[96:97]
	v_pk_fma_f32 v[110:111], v[80:81], v[62:63], v[110:111]
	v_pk_fma_f32 v[106:107], v[80:81], v[58:59], v[106:107]
	v_pk_fma_f32 v[80:81], v[80:81], v[54:55], v[92:93]
	v_rcp_f32_e32 v75, v243
	v_pk_fma_f32 v[102:103], v[76:77], v[102:103], v[110:111]
	v_pk_fma_f32 v[106:107], v[76:77], v[62:63], v[106:107]
	v_pk_fma_f32 v[114:115], v[76:77], v[58:59], v[80:81]
	v_pk_add_f32 v[244:245], v[244:245], v[250:251]
	v_rcp_f32_e32 v76, v244
	v_rcp_f32_e32 v77, v245
	v_exp_f32_e32 v246, v98
	v_exp_f32_e32 v247, v99
	v_pk_mul_f32 v[118:119], v[100:101], v[74:75]
	v_pk_add_f32 v[246:247], v[246:247], v[250:251]
	v_rcp_f32_e32 v74, v246
	v_exp_f32_e32 v248, v102
	v_exp_f32_e32 v249, v103
	v_rcp_f32_e32 v75, v247
	v_pk_mul_f32 v[120:121], v[104:105], v[76:77]
	v_pk_add_f32 v[248:249], v[248:249], v[250:251]
	v_rcp_f32_e32 v76, v248
	v_rcp_f32_e32 v77, v249
	v_exp_f32_e32 v240, v108
	v_exp_f32_e32 v241, v109
	v_pk_mul_f32 v[122:123], v[98:99], v[74:75]
	v_pk_add_f32 v[240:241], v[240:241], v[250:251]
	v_rcp_f32_e32 v74, v240
	v_exp_f32_e32 v242, v106
	v_exp_f32_e32 v243, v107
	v_rcp_f32_e32 v75, v241
	v_pk_add_f32 v[242:243], v[242:243], v[250:251]
	v_rcp_f32_e32 v78, v242
	v_exp_f32_e32 v244, v116
	v_exp_f32_e32 v245, v117
	v_rcp_f32_e32 v79, v243
	v_pk_add_f32 v[244:245], v[244:245], v[250:251]
	v_rcp_f32_e32 v124, v244
	v_exp_f32_e32 v246, v114
	v_exp_f32_e32 v247, v115
	v_rcp_f32_e32 v125, v245
	v_pk_add_f32 v[246:247], v[246:247], v[250:251]
	v_rcp_f32_e32 v126, v246
	v_rcp_f32_e32 v127, v247
	v_pk_mul_f32 v[148:149], v[102:103], v[76:77]
	v_pk_mul_f32 v[150:151], v[108:109], v[74:75]
	v_pk_mul_f32 v[154:155], v[106:107], v[78:79]
	ds_read_b128 v[98:101], v195 offset:128
	ds_read_b128 v[102:105], v195 offset:384
	ds_read_b128 v[106:109], v195 offset:640
	ds_read_b128 v[110:113], v195 offset:896
	v_pk_mul_f32 v[90:91], v[44:45], v[88:89] op_sel_hi:[1,0]
	v_pk_mul_f32 v[78:79], v[32:33], v[82:83] op_sel_hi:[1,0]
	v_pk_mul_f32 v[94:95], v[36:37], v[84:85] op_sel_hi:[1,0]
	v_pk_mul_f32 v[74:75], v[40:41], v[86:87] op_sel_hi:[1,0]
	v_mov_b32_dpp v32, v78 row_shr:1 row_mask:0xf bank_mask:0xf bound_ctrl:1
	v_mov_b32_dpp v33, v79 row_shr:1 row_mask:0xf bank_mask:0xf bound_ctrl:1
	s_waitcnt lgkmcnt(0)
;     __device__ __forceinline__ void operator()(f32x4 (&acc)[2][2][4][2], const pg8::Unit& u, int wr, int wc, int fr, int fq) const {
;     ...
;                 {   const PG8_LAS unsigned char* wq = wl + (8 * fq + 4 * n) * 4;
;                     const f32x4 w0 = *(const PG8_LAS f32x4*)(wq), w1 = *(const PG8_LAS f32x4*)(wq + 256), w2 = *(const PG8_LAS f32x4*)(wq + 512), bb = *(const PG8_LAS f32x4*)(wq + 768);
;                     const f32x4 x0 = acc[ai][0][0][n] * rstd[0], x1 = acc[ai][0][1][n] * rstd[1], x2 = acc[ai][0][2][n] * rstd[2], x3 = acc[ai][0][3][n] * rstd[3];
;                     acc[ai][0][0][n] = x0; acc[ai][0][1][n] = x1; acc[ai][0][2][n] = x2; acc[ai][0][3][n] = x3;
;                     f32x4 p1, p2;
; #pragma unroll
;                     for (int c = 0; c < 4; ++c) { p1[c] = row_up1(x3[c]); p2[c] = row_up1(x2[c]); }
;                     g[0] = bb + w2 * x0 + w1 * p1 + w0 * p2; g[1] = bb + w2 * x1 + w1 * x0 + w0 * p1;
;                     g[2] = bb + w2 * x2 + w1 * x1 + w0 * x0; g[3] = bb + w2 * x3 + w1 * x2 + w0 * x1;
; #pragma unroll
;                     for (int m = 0; m < 4; ++m)
; #pragma unroll
;                         for (int c = 0; c < 4; ++c) g[m][c] = siluf_(g[m][c]);
;                 }
;                 __builtin_amdgcn_sched_barrier(0);
;                 {   const PG8_LAS unsigned char* wq = wl + 128 + (8 * fq + 4 * n) * 4;
;                     const f32x4 w0 = *(const PG8_LAS f32x4*)(wq), w1 = *(const PG8_LAS f32x4*)(wq + 256), w2 = *(const PG8_LAS f32x4*)(wq + 512), bb = *(const PG8_LAS f32x4*)(wq + 768);
;                     const f32x4 x0 = acc[ai][1][0][n] * rstd[0], x1 = acc[ai][1][1][n] * rstd[1], x2 = acc[ai][1][2][n] * rstd[2], x3 = acc[ai][1][3][n] * rstd[3];
;                     acc[ai][1][0][n] = x0; acc[ai][1][1][n] = x1; acc[ai][1][2][n] = x2; acc[ai][1][3][n] = x3;
;                     f32x4 p1, p2;
; #pragma unroll
;                     for (int c = 0; c < 4; ++c) { p1[c] = row_up1(x3[c]); p2[c] = row_up1(x2[c]); }
;                     g[0] *= bb + w2 * x0 + w1 * p1 + w0 * p2; g[1] *= bb + w2 * x1 + w1 * x0 + w0 * p1;
;                     g[2] *= bb + w2 * x2 + w1 * x1 + w0 * x0; g[3] *= bb + w2 * x3 + w1 * x2 + w0 * x1;
;                 }
; #pragma unroll
;                 for (int m = 0; m < 4; ++m) { pk[n][m].x = pk2(g[m][0], g[m][1]); pk[n][m].y = pk2(g[m][2], g[m][3]); }
	v_pk_fma_f32 v[44:45], v[90:91], v[106:107], v[110:111]
	v_pk_mul_f32 v[80:81], v[34:35], v[82:83] op_sel_hi:[1,0]
	v_mov_b32_dpp v34, v94 row_shr:1 row_mask:0xf bank_mask:0xf bound_ctrl:1
	v_mov_b32_dpp v35, v95 row_shr:1 row_mask:0xf bank_mask:0xf bound_ctrl:1
	v_pk_fma_f32 v[44:45], v[102:103], v[32:33], v[44:45]
	v_pk_mul_f32 v[92:93], v[46:47], v[88:89] op_sel_hi:[1,0]
	v_pk_fma_f32 v[34:35], v[98:99], v[34:35], v[44:45]
	v_pk_fma_f32 v[44:45], v[74:75], v[106:107], v[110:111]
	v_pk_mul_f32 v[96:97], v[38:39], v[84:85] op_sel_hi:[1,0]
	v_mov_b32_dpp v36, v80 row_shr:1 row_mask:0xf bank_mask:0xf bound_ctrl:1
	v_mov_b32_dpp v37, v81 row_shr:1 row_mask:0xf bank_mask:0xf bound_ctrl:1
	v_pk_fma_f32 v[46:47], v[92:93], v[108:109], v[112:113]
	v_pk_fma_f32 v[44:45], v[90:91], v[102:103], v[44:45]
	v_pk_mul_f32 v[76:77], v[42:43], v[86:87] op_sel_hi:[1,0]
	v_mov_b32_dpp v38, v96 row_shr:1 row_mask:0xf bank_mask:0xf bound_ctrl:1
	v_mov_b32_dpp v39, v97 row_shr:1 row_mask:0xf bank_mask:0xf bound_ctrl:1
	v_pk_fma_f32 v[46:47], v[104:105], v[36:37], v[46:47]
	v_pk_fma_f32 v[32:33], v[98:99], v[32:33], v[44:45]
	v_pk_fma_f32 v[44:45], v[94:95], v[106:107], v[110:111]
	v_pk_fma_f32 v[38:39], v[100:101], v[38:39], v[46:47]
	v_pk_fma_f32 v[46:47], v[76:77], v[108:109], v[112:113]
	v_pk_fma_f32 v[44:45], v[74:75], v[102:103], v[44:45]
	v_pk_fma_f32 v[46:47], v[92:93], v[104:105], v[46:47]
	v_pk_fma_f32 v[44:45], v[90:91], v[98:99], v[44:45]
	v_pk_mul_f32 v[42:43], v[114:115], v[126:127]
	v_pk_fma_f32 v[36:37], v[100:101], v[36:37], v[46:47]
	v_pk_fma_f32 v[46:47], v[96:97], v[108:109], v[112:113]
	v_pk_mul_f32 v[114:115], v[44:45], v[150:151]
	v_pk_fma_f32 v[44:45], v[78:79], v[106:107], v[110:111]
	v_pk_fma_f32 v[106:107], v[80:81], v[108:109], v[112:113]
	v_pk_fma_f32 v[46:47], v[76:77], v[104:105], v[46:47]
	v_pk_fma_f32 v[104:105], v[96:97], v[104:105], v[106:107]
	v_pk_fma_f32 v[44:45], v[94:95], v[102:103], v[44:45]
	v_pk_mul_f32 v[40:41], v[116:117], v[124:125]
	v_pk_fma_f32 v[46:47], v[92:93], v[100:101], v[46:47]
	v_pk_fma_f32 v[44:45], v[74:75], v[98:99], v[44:45]
	v_pk_fma_f32 v[98:99], v[76:77], v[100:101], v[104:105]
	v_pk_mul_f32 v[38:39], v[120:121], v[38:39]
	v_pk_mul_f32 v[34:35], v[118:119], v[34:35]
	v_pk_mul_f32 v[36:37], v[148:149], v[36:37]
	v_pk_mul_f32 v[32:33], v[122:123], v[32:33]
	v_pk_mul_f32 v[46:47], v[46:47], v[154:155]
	v_pk_mul_f32 v[42:43], v[98:99], v[42:43]
	v_pk_mul_f32 v[98:99], v[44:45], v[40:41]
	v_cvt_pk_bf16_f32 v44, v34, v35
	v_cvt_pk_bf16_f32 v45, v38, v39
	v_cvt_pk_bf16_f32 v40, v32, v33
	v_cvt_pk_bf16_f32 v41, v36, v37
	v_cvt_pk_bf16_f32 v36, v114, v115
	v_cvt_pk_bf16_f32 v37, v46, v47
	s_nop 0
	v_cvt_pk_bf16_f32 v32, v98, v99
	v_cvt_pk_bf16_f32 v33, v42, v43
	ds_read_b128 v[102:105], v195 offset:16
	ds_read_b128 v[106:109], v195 offset:272
	ds_read_b128 v[110:113], v195 offset:528
	ds_read_b128 v[114:117], v195 offset:784
	v_pk_mul_f32 v[98:99], v[16:17], v[88:89] op_sel_hi:[1,0]
	v_pk_mul_f32 v[16:17], v[20:21], v[86:87] op_sel_hi:[1,0]
	v_pk_mul_f32 v[20:21], v[28:29], v[82:83] op_sel_hi:[1,0]
	v_pk_mul_f32 v[24:25], v[24:25], v[84:85] op_sel_hi:[1,0]
	s_waitcnt lgkmcnt(0)
	v_pk_fma_f32 v[46:47], v[98:99], v[110:111], v[114:115]
	v_mov_b32_dpp v28, v20 row_shr:1 row_mask:0xf bank_mask:0xf bound_ctrl:1
	v_mov_b32_dpp v29, v21 row_shr:1 row_mask:0xf bank_mask:0xf bound_ctrl:1
	v_pk_mul_f32 v[100:101], v[18:19], v[88:89] op_sel_hi:[1,0]
	v_pk_mul_f32 v[18:19], v[22:23], v[86:87] op_sel_hi:[1,0]
	v_pk_mul_f32 v[22:23], v[30:31], v[82:83] op_sel_hi:[1,0]
	v_mov_b32_dpp v30, v24 row_shr:1 row_mask:0xf bank_mask:0xf bound_ctrl:1
	v_mov_b32_dpp v31, v25 row_shr:1 row_mask:0xf bank_mask:0xf bound_ctrl:1
	v_pk_fma_f32 v[46:47], v[106:107], v[28:29], v[46:47]
	v_pk_mul_f32 v[26:27], v[26:27], v[84:85] op_sel_hi:[1,0]
	v_pk_fma_f32 v[30:31], v[102:103], v[30:31], v[46:47]
	v_pk_fma_f32 v[46:47], v[16:17], v[110:111], v[114:115]
	v_exp_f32_e32 v248, v30
	v_exp_f32_e32 v249, v31
	v_mov_b32_dpp v34, v22 row_shr:1 row_mask:0xf bank_mask:0xf bound_ctrl:1
	v_mov_b32_dpp v35, v23 row_shr:1 row_mask:0xf bank_mask:0xf bound_ctrl:1
	v_pk_fma_f32 v[42:43], v[100:101], v[112:113], v[116:117]
	v_pk_fma_f32 v[46:47], v[98:99], v[106:107], v[46:47]
	v_mov_b32_dpp v38, v26 row_shr:1 row_mask:0xf bank_mask:0xf bound_ctrl:1
	v_mov_b32_dpp v39, v27 row_shr:1 row_mask:0xf bank_mask:0xf bound_ctrl:1
	v_pk_fma_f32 v[42:43], v[108:109], v[34:35], v[42:43]
	v_pk_fma_f32 v[28:29], v[102:103], v[28:29], v[46:47]
	v_pk_fma_f32 v[46:47], v[24:25], v[110:111], v[114:115]
	v_pk_fma_f32 v[110:111], v[20:21], v[110:111], v[114:115]
	v_pk_fma_f32 v[38:39], v[104:105], v[38:39], v[42:43]
	v_pk_fma_f32 v[46:47], v[16:17], v[106:107], v[46:47]
	v_pk_fma_f32 v[106:107], v[24:25], v[106:107], v[110:111]
	v_pk_fma_f32 v[46:47], v[98:99], v[102:103], v[46:47]
	v_pk_fma_f32 v[120:121], v[16:17], v[102:103], v[106:107]
	v_pk_add_f32 v[248:249], v[248:249], v[250:251]
	v_rcp_f32_e32 v102, v248
	v_exp_f32_e32 v240, v38
	v_pk_fma_f32 v[42:43], v[18:19], v[112:113], v[116:117]
	v_exp_f32_e32 v241, v39
	v_pk_fma_f32 v[42:43], v[100:101], v[108:109], v[42:43]
	v_rcp_f32_e32 v103, v249
	v_pk_fma_f32 v[34:35], v[104:105], v[34:35], v[42:43]
	v_pk_fma_f32 v[42:43], v[26:27], v[112:113], v[116:117]
; #define PG8_LAS __attribute__((address_space(3)))
; __device__ __forceinline__ unsigned pk2(float a, float b) { return pg8::cvt_pk_bf16(a, b); }
; __device__ __forceinline__ float row_up1(float v) { return dpp_mov<0x111>(v); }
; __device__ __forceinline__ float siluf_(float x) { return x * __builtin_amdgcn_rcpf(1.0f + __builtin_amdgcn_exp2f(x * -1.4426950408889634f)); }
;     __device__ __forceinline__ void operator()(f32x4 (&acc)[2][2][4][2], const pg8::Unit& u, int wr, int wc, int fr, int fq) const {
;     ...
;                     g[0] = bb + w2 * x0 + w1 * p1 + w0 * p2; g[1] = bb + w2 * x1 + w1 * x0 + w0 * p1;
;                     g[2] = bb + w2 * x2 + w1 * x1 + w0 * x0; g[3] = bb + w2 * x3 + w1 * x2 + w0 * x1;
; #pragma unroll
;                     for (int m = 0; m < 4; ++m)
; #pragma unroll
;                         for (int c = 0; c < 4; ++c) g[m][c] = siluf_(g[m][c]);
;                 }
;                 __builtin_amdgcn_sched_barrier(0);
;                 {   const PG8_LAS unsigned char* wq = wl + 128 + (8 * fq + 4 * n) * 4;
;                     const f32x4 w0 = *(const PG8_LAS f32x4*)(wq), w1 = *(const PG8_LAS f32x4*)(wq + 256), w2 = *(const PG8_LAS f32x4*)(wq + 512), bb = *(const PG8_LAS f32x4*)(wq + 768);
;                     const f32x4 x0 = acc[ai][1][0][n] * rstd[0], x1 = acc[ai][1][1][n] * rstd[1], x2 = acc[ai][1][2][n] * rstd[2], x3 = acc[ai][1][3][n] * rstd[3];
;                     acc[ai][1][0][n] = x0; acc[ai][1][1][n] = x1; acc[ai][1][2][n] = x2; acc[ai][1][3][n] = x3;
;                     f32x4 p1, p2;
; #pragma unroll
;                     for (int c = 0; c < 4; ++c) { p1[c] = row_up1(x3[c]); p2[c] = row_up1(x2[c]); }
;                     g[0] *= bb + w2 * x0 + w1 * p1 + w0 * p2; g[1] *= bb + w2 * x1 + w1 * x0 + w0 * p1;
;                     g[2] *= bb + w2 * x2 + w1 * x1 + w0 * x0; g[3] *= bb + w2 * x3 + w1 * x2 + w0 * x1;
;                 }
; #pragma unroll
;                 for (int m = 0; m < 4; ++m) { pk[n][m].x = pk2(g[m][0], g[m][1]); pk[n][m].y = pk2(g[m][2], g[m][3]); }
;                 __builtin_amdgcn_sched_barrier(0);
;             }
; #pragma unroll
;             for (int m = 0; m < 4; ++m) if (fr != 0 || m >= 2) {
;                 u32x4 w; w.x = pk[0][m].x; w.y = pk[0][m].y; w.z = pk[1][m].x; w.w = pk[1][m].y;
;                 *(u32x4*)(ACT + (size_t)(tb + m) * DFF + colj) = w; }
	v_pk_fma_f32 v[112:113], v[22:23], v[112:113], v[116:117]
	v_pk_fma_f32 v[42:43], v[18:19], v[108:109], v[42:43]
	v_pk_fma_f32 v[108:109], v[26:27], v[108:109], v[112:113]
	v_pk_fma_f32 v[42:43], v[100:101], v[104:105], v[42:43]
	v_pk_fma_f32 v[118:119], v[18:19], v[104:105], v[108:109]
	v_pk_add_f32 v[240:241], v[240:241], v[250:251]
	v_rcp_f32_e32 v104, v240
	v_rcp_f32_e32 v105, v241
	v_exp_f32_e32 v242, v34
	v_pk_mul_f32 v[122:123], v[30:31], v[102:103]
	v_exp_f32_e32 v243, v35
	v_exp_f32_e32 v244, v28
	v_exp_f32_e32 v245, v29
	v_pk_add_f32 v[242:243], v[242:243], v[250:251]
	v_rcp_f32_e32 v102, v242
	v_pk_add_f32 v[244:245], v[244:245], v[250:251]
	v_rcp_f32_e32 v103, v243
	v_rcp_f32_e32 v30, v244
	v_rcp_f32_e32 v31, v245
	v_exp_f32_e32 v246, v46
	v_exp_f32_e32 v247, v47
	v_pk_mul_f32 v[124:125], v[28:29], v[30:31]
	v_pk_add_f32 v[246:247], v[246:247], v[250:251]
	v_exp_f32_e32 v248, v120
	v_exp_f32_e32 v249, v121
	v_exp_f32_e32 v240, v42
	v_exp_f32_e32 v241, v43
	v_pk_add_f32 v[248:249], v[248:249], v[250:251]
	v_rcp_f32_e32 v126, v248
	v_pk_add_f32 v[240:241], v[240:241], v[250:251]
	v_exp_f32_e32 v242, v118
	v_rcp_f32_e32 v28, v246
	v_rcp_f32_e32 v29, v247
	v_rcp_f32_e32 v30, v240
	v_rcp_f32_e32 v31, v241
	v_exp_f32_e32 v243, v119
	v_rcp_f32_e32 v127, v249
	v_pk_mul_f32 v[38:39], v[38:39], v[104:105]
	v_pk_add_f32 v[242:243], v[242:243], v[250:251]
	v_rcp_f32_e32 v148, v242
	v_pk_mul_f32 v[34:35], v[34:35], v[102:103]
	v_pk_mul_f32 v[46:47], v[46:47], v[28:29]
	v_pk_mul_f32 v[42:43], v[42:43], v[30:31]
	v_rcp_f32_e32 v149, v243
	ds_read_b128 v[102:105], v195 offset:144
	ds_read_b128 v[106:109], v195 offset:400
	ds_read_b128 v[110:113], v195 offset:656
	ds_read_b128 v[114:117], v195 offset:912
	v_pk_mul_f32 v[30:31], v[2:3], v[88:89] op_sel_hi:[1,0]
	v_pk_mul_f32 v[28:29], v[0:1], v[88:89] op_sel_hi:[1,0]
	v_pk_mul_f32 v[2:3], v[6:7], v[86:87] op_sel_hi:[1,0]
	v_pk_mul_f32 v[0:1], v[4:5], v[86:87] op_sel_hi:[1,0]
	v_pk_mul_f32 v[6:7], v[14:15], v[82:83] op_sel_hi:[1,0]
	v_pk_mul_f32 v[4:5], v[12:13], v[82:83] op_sel_hi:[1,0]
	v_pk_mul_f32 v[10:11], v[10:11], v[84:85] op_sel_hi:[1,0]
	v_pk_mul_f32 v[8:9], v[8:9], v[84:85] op_sel_hi:[1,0]
	v_mov_b32_dpp v12, v4 row_shr:1 row_mask:0xf bank_mask:0xf bound_ctrl:1
	v_mov_b32_dpp v13, v5 row_shr:1 row_mask:0xf bank_mask:0xf bound_ctrl:1
	v_mov_b32_dpp v82, v6 row_shr:1 row_mask:0xf bank_mask:0xf bound_ctrl:1
	v_mov_b32_dpp v83, v7 row_shr:1 row_mask:0xf bank_mask:0xf bound_ctrl:1
	v_pk_mul_f32 v[86:87], v[120:121], v[126:127]
	v_pk_mul_f32 v[88:89], v[118:119], v[148:149]
	s_waitcnt lgkmcnt(0)
	v_pk_fma_f32 v[118:119], v[28:29], v[110:111], v[114:115]
	v_pk_fma_f32 v[120:121], v[30:31], v[112:113], v[116:117]
	v_mov_b32_dpp v14, v8 row_shr:1 row_mask:0xf bank_mask:0xf bound_ctrl:1
	v_mov_b32_dpp v15, v9 row_shr:1 row_mask:0xf bank_mask:0xf bound_ctrl:1
	v_mov_b32_dpp v84, v10 row_shr:1 row_mask:0xf bank_mask:0xf bound_ctrl:1
	v_mov_b32_dpp v85, v11 row_shr:1 row_mask:0xf bank_mask:0xf bound_ctrl:1
	v_pk_fma_f32 v[120:121], v[108:109], v[82:83], v[120:121]
	v_pk_fma_f32 v[118:119], v[106:107], v[12:13], v[118:119]
	v_pk_fma_f32 v[84:85], v[104:105], v[84:85], v[120:121]
	v_pk_fma_f32 v[14:15], v[102:103], v[14:15], v[118:119]
	v_pk_fma_f32 v[118:119], v[2:3], v[112:113], v[116:117]
	v_pk_mul_f32 v[38:39], v[38:39], v[84:85]
	v_pk_fma_f32 v[84:85], v[0:1], v[110:111], v[114:115]
	v_pk_fma_f32 v[118:119], v[30:31], v[108:109], v[118:119]
	v_pk_fma_f32 v[84:85], v[28:29], v[106:107], v[84:85]
	v_pk_fma_f32 v[82:83], v[104:105], v[82:83], v[118:119]
	v_pk_fma_f32 v[12:13], v[102:103], v[12:13], v[84:85]
	v_pk_mul_f32 v[34:35], v[34:35], v[82:83]
	v_pk_fma_f32 v[82:83], v[8:9], v[110:111], v[114:115]
	v_pk_fma_f32 v[84:85], v[10:11], v[112:113], v[116:117]
	v_pk_fma_f32 v[82:83], v[0:1], v[106:107], v[82:83]
	v_pk_fma_f32 v[84:85], v[2:3], v[108:109], v[84:85]
	v_pk_fma_f32 v[82:83], v[28:29], v[102:103], v[82:83]
	v_pk_fma_f32 v[84:85], v[30:31], v[104:105], v[84:85]
	v_pk_mul_f32 v[82:83], v[46:47], v[82:83]
	v_pk_mul_f32 v[84:85], v[42:43], v[84:85]
	v_pk_fma_f32 v[42:43], v[4:5], v[110:111], v[114:115]
	v_pk_fma_f32 v[46:47], v[6:7], v[112:113], v[116:117]
	v_pk_fma_f32 v[42:43], v[8:9], v[106:107], v[42:43]
	v_pk_fma_f32 v[46:47], v[10:11], v[108:109], v[46:47]
	v_pk_fma_f32 v[42:43], v[0:1], v[102:103], v[42:43]
	v_pk_fma_f32 v[46:47], v[2:3], v[104:105], v[46:47]
	v_pk_mul_f32 v[14:15], v[122:123], v[14:15]
	v_pk_mul_f32 v[12:13], v[124:125], v[12:13]
	v_pk_mul_f32 v[88:89], v[88:89], v[46:47]
	v_pk_mul_f32 v[86:87], v[86:87], v[42:43]
	v_cvt_pk_bf16_f32 v46, v14, v15
	v_cvt_pk_bf16_f32 v47, v38, v39
	v_cvt_pk_bf16_f32 v42, v12, v13
	v_cvt_pk_bf16_f32 v43, v34, v35
	v_cvt_pk_bf16_f32 v38, v82, v83
	v_cvt_pk_bf16_f32 v39, v84, v85
	s_nop 0
	v_cvt_pk_bf16_f32 v34, v86, v87
	v_cvt_pk_bf16_f32 v35, v88, v89
	s_and_saveexec_b64 s[8:9], s[0:1]
	s_cbranch_execz .LBB0_756
	v_mov_b64_e32 v[12:13], s[22:23]
	v_mad_i64_i32 v[14:15], s[10:11], v66, s56, v[12:13]
	v_mad_i64_i32 v[12:13], s[10:11], v68, s56, v[12:13]
	v_lshl_add_u64 v[14:15], v[14:15], 0, v[64:65]
	v_lshl_add_u64 v[12:13], v[12:13], 0, v[64:65]
	global_store_dwordx4 v[14:15], v[44:47], off
	global_store_dwordx4 v[12:13], v[40:43], off
